# saddr form: P8 epilogue stores (address minus ws base) and the P1/P8 tail weight-conversion loops (32 loads + 8 stores per item relative to copied SGPR bases)
# baseline (speedup 1.0000x reference)
.LBB0_151:
	s_lshl_b32 s16, s36, 14
	s_add_i32 s22, s16, 0
	s_sext_i32_i16 s16, s30
	s_lshl_b32 s16, s16, 6
	s_ashr_i32 s17, s16, 31
	s_mul_i32 s21, s14, s17
	s_mul_hi_u32 s30, s14, s16
	s_add_i32 s21, s30, s21
	s_mul_i32 s15, s15, s16
	s_add_i32 s31, s21, s15
	s_mul_i32 s30, s14, s16
	s_lshl_b64 s[30:31], s[30:31], 2
	s_add_u32 s15, s12, s30
	s_addc_u32 s30, s13, s31
	s_ashr_i32 s21, s20, 31
	s_lshl_b64 s[12:13], s[20:21], 2
	v_and_b32_e32 v67, 15, v66
	s_add_u32 s12, s15, s12
	v_lshrrev_b32_e32 v69, 3, v0
	v_bfe_u32 v130, v0, 3, 3
	s_addc_u32 s13, s30, s13
	v_and_b32_e32 v131, 48, v66
	v_lshlrev_b32_e32 v0, 4, v67
	s_mov_b64 s[78:79], s[12:13]
	v_mov_b32_e32 v58, v0
	v_mul_u32_u24_e32 v0, s14, v131
	v_lshlrev_b32_e32 v0, 2, v0
	v_or_b32_e32 v133, 1, v131
	v_add_u32_e32 v2, v58, v0
	v_mul_u32_u24_e32 v0, s14, v133
	v_lshlrev_b32_e32 v0, 2, v0
	v_or_b32_e32 v135, 2, v131
	v_add_u32_e32 v4, v58, v0
	v_mul_u32_u24_e32 v0, s14, v135
	v_lshlrev_b32_e32 v0, 2, v0
	v_or_b32_e32 v137, 3, v131
	v_add_u32_e32 v10, v58, v0
	v_mul_u32_u24_e32 v0, s14, v137
	v_lshlrev_b32_e32 v0, 2, v0
	v_or_b32_e32 v139, 4, v131
	v_add_u32_e32 v12, v58, v0
	v_mul_u32_u24_e32 v0, s14, v139
	v_lshlrev_b32_e32 v0, 2, v0
	v_or_b32_e32 v141, 5, v131
	v_add_u32_e32 v18, v58, v0
	v_mul_u32_u24_e32 v0, s14, v141
	v_lshlrev_b32_e32 v0, 2, v0
	v_or_b32_e32 v143, 6, v131
	v_add_u32_e32 v20, v58, v0
	v_mul_u32_u24_e32 v0, s14, v143
	v_lshlrev_b32_e32 v0, 2, v0
	v_or_b32_e32 v145, 7, v131
	v_add_u32_e32 v26, v58, v0
	v_mul_u32_u24_e32 v0, s14, v145
	v_lshlrev_b32_e32 v0, 2, v0
	v_or_b32_e32 v148, 8, v131
	v_add_u32_e32 v28, v58, v0
	v_mul_u32_u24_e32 v0, s14, v148
	v_lshlrev_b32_e32 v0, 2, v0
	v_or_b32_e32 v149, 9, v131
	v_add_u32_e32 v34, v58, v0
	v_mul_u32_u24_e32 v0, s14, v149
	v_lshlrev_b32_e32 v0, 2, v0
	v_or_b32_e32 v150, 10, v131
	v_add_u32_e32 v36, v58, v0
	v_mul_u32_u24_e32 v0, s14, v150
	v_lshlrev_b32_e32 v0, 2, v0
	v_or_b32_e32 v151, 11, v131
	v_add_u32_e32 v42, v58, v0
	v_mul_u32_u24_e32 v0, s14, v151
	v_lshlrev_b32_e32 v0, 2, v0
	v_or_b32_e32 v152, 12, v131
	v_add_u32_e32 v44, v58, v0
	v_mul_u32_u24_e32 v0, s14, v152
	v_lshlrev_b32_e32 v0, 2, v0
	v_or_b32_e32 v153, 13, v131
	v_add_u32_e32 v50, v58, v0
	v_mul_u32_u24_e32 v0, s14, v153
	v_lshlrev_b32_e32 v0, 2, v0
	v_or_b32_e32 v154, 14, v131
	v_add_u32_e32 v52, v58, v0
	v_mul_u32_u24_e32 v0, s14, v154
	v_lshlrev_b32_e32 v0, 2, v0
	v_or_b32_e32 v155, 15, v131
	v_add_u32_e32 v60, v58, v0
	v_mul_u32_u24_e32 v0, s14, v155
	v_lshlrev_b32_e32 v0, 2, v0
	v_add_u32_e32 v58, v58, v0
	global_load_dwordx4 v[6:9], v2, s[78:79] nt
	s_nop 0
	global_load_dwordx4 v[2:5], v4, s[78:79] nt
	s_nop 0
	global_load_dwordx4 v[14:17], v10, s[78:79] nt
	s_nop 0
	global_load_dwordx4 v[10:13], v12, s[78:79] nt
	s_nop 0
	global_load_dwordx4 v[22:25], v18, s[78:79] nt
	s_nop 0
	global_load_dwordx4 v[18:21], v20, s[78:79] nt
	s_nop 0
	global_load_dwordx4 v[30:33], v26, s[78:79] nt
	s_nop 0
	global_load_dwordx4 v[26:29], v28, s[78:79] nt
	s_nop 0
	global_load_dwordx4 v[38:41], v34, s[78:79] nt
	s_nop 0
	global_load_dwordx4 v[34:37], v36, s[78:79] nt
	s_nop 0
	global_load_dwordx4 v[46:49], v42, s[78:79] nt
	s_nop 0
	global_load_dwordx4 v[42:45], v44, s[78:79] nt
	s_nop 0
	global_load_dwordx4 v[54:57], v50, s[78:79] nt
	s_nop 0
	global_load_dwordx4 v[50:53], v52, s[78:79] nt
	s_nop 0
	global_load_dwordx4 v[62:65], v60, s[78:79] nt
	s_nop 0
	global_load_dwordx4 v[58:61], v58, s[78:79] nt
	s_ashr_i32 s12, s23, 31
	s_mul_hi_u32 s13, s23, s48
	s_mul_i32 s12, s12, s48
	s_add_i32 s13, s13, s12
	s_mul_i32 s12, s23, s48
	s_lshl_b64 s[12:13], s[12:13], 1
	v_and_b32_e32 v68, 6, v69
	v_and_b32_e32 v70, 7, v66
	v_or_b32_e32 v132, 8, v130
	v_or_b32_e32 v134, 16, v130
	v_or_b32_e32 v136, 24, v130
	v_or_b32_e32 v140, 40, v130
	v_or_b32_e32 v142, 48, v130
	v_or_b32_e32 v144, 56, v130
	s_add_u32 s12, s0, s12
	v_bitop3_b32 v71, v69, v70, 6 bitop3:0x6c
	v_bitop3_b32 v68, v68, v70, 1 bitop3:0x36
	v_bfe_u32 v69, v69, 2, 1
	v_lshrrev_b32_e32 v74, 2, v132
	v_lshrrev_b32_e32 v76, 2, v134
	v_lshrrev_b32_e32 v78, 2, v136
	v_lshrrev_b32_e32 v81, 2, v140
	v_lshrrev_b32_e32 v83, 2, v142
	v_lshrrev_b32_e32 v85, 2, v144
	s_addc_u32 s13, s1, s13
	s_lshl_b64 s[0:1], s[16:17], 1
	v_lshlrev_b32_e32 v70, 4, v68
	v_lshlrev_b32_e32 v68, 3, v66
	v_xor_b32_e32 v69, v69, v66
	v_xor_b32_e32 v74, v74, v66
	v_xor_b32_e32 v76, v76, v66
	v_xor_b32_e32 v78, v78, v66
	v_xor_b32_e32 v81, v81, v66
	v_xor_b32_e32 v83, v83, v66
	v_xor_b32_e32 v66, v85, v66
	s_add_u32 s0, s12, s0
	v_lshlrev_b32_e32 v69, 4, v69
	v_lshlrev_b32_e32 v74, 4, v74
	v_lshlrev_b32_e32 v76, 4, v76
	v_lshlrev_b32_e32 v78, 4, v78
	v_or_b32_e32 v138, 32, v130
	v_lshlrev_b32_e32 v81, 4, v81
	v_lshlrev_b32_e32 v83, 4, v83
	v_lshlrev_b32_e32 v66, 4, v66
	v_lshlrev_b32_e32 v0, 2, v67
	s_addc_u32 s1, s13, s1
	v_lshl_add_u32 v67, v67, 9, s22
	v_lshlrev_b32_e32 v71, 4, v71
	v_and_b32_e32 v68, 56, v68
	v_lshl_add_u32 v72, v130, 7, s22
	v_and_b32_e32 v69, 0x70, v69
	v_lshl_add_u32 v73, v132, 7, s22
	v_and_b32_e32 v74, 0x70, v74
	v_lshl_add_u32 v75, v134, 7, s22
	v_and_b32_e32 v76, 0x70, v76
	v_lshl_add_u32 v77, v136, 7, s22
	v_and_b32_e32 v78, 0x70, v78
	v_lshl_add_u32 v79, v138, 7, s22
	v_lshl_add_u32 v80, v140, 7, s22
	v_and_b32_e32 v81, 0x70, v81
	v_lshl_add_u32 v82, v142, 7, s22
	v_and_b32_e32 v83, 0x70, v83
	v_lshl_add_u32 v84, v144, 7, s22
	v_and_b32_e32 v66, 0x70, v66
	s_add_i32 s49, s2, 0x300
	v_lshlrev_b32_e32 v0, 2, v0
	v_add_u32_e32 v156, v67, v71
	v_add_u32_e32 v157, v67, v70
	v_lshlrev_b32_e32 v146, 1, v68
	v_add_u32_e32 v158, v72, v69
	v_add_u32_e32 v159, v73, v74
	v_add_u32_e32 v160, v75, v76
	v_add_u32_e32 v161, v77, v78
	v_add_u32_e32 v162, v79, v69
	v_add_u32_e32 v163, v80, v81
	v_add_u32_e32 v164, v82, v83
	v_add_u32_e32 v165, v84, v66
	s_mov_b64 s[12:13], s[0:1]
	s_mov_b32 s51, s48
	s_branch .LBB0_154
.LBB0_152:
	s_sext_i32_i16 s20, s31
	s_lshl_b32 s20, s20, 6
	s_ashr_i32 s21, s20, 31
	s_mul_i32 s23, s16, s21
	s_mul_hi_u32 s31, s16, s20
	s_add_i32 s23, s31, s23
	s_mul_i32 s17, s17, s20
	s_add_i32 s37, s23, s17
	s_mul_i32 s36, s16, s20
	s_lshl_b64 s[36:37], s[36:37], 2
	s_add_u32 s17, s14, s36
	s_addc_u32 s31, s15, s37
	s_ashr_i32 s23, s22, 31
	s_lshl_b64 s[14:15], s[22:23], 2
	s_add_u32 s14, s17, s14
	s_addc_u32 s15, s31, s15
	v_mul_u32_u24_e32 v66, s16, v131
	v_mul_u32_u24_e32 v68, s16, v133
	v_mul_u32_u24_e32 v74, s16, v135
	v_mul_u32_u24_e32 v76, s16, v137
	v_mul_u32_u24_e32 v82, s16, v139
	v_mul_u32_u24_e32 v84, s16, v141
	v_mul_u32_u24_e32 v90, s16, v143
	v_mul_u32_u24_e32 v92, s16, v145
	v_mul_u32_u24_e32 v98, s16, v148
	v_mul_u32_u24_e32 v100, s16, v149
	v_mul_u32_u24_e32 v106, s16, v150
	v_mul_u32_u24_e32 v108, s16, v151
	v_mul_u32_u24_e32 v114, s16, v152
	v_mul_u32_u24_e32 v116, s16, v153
	v_mul_u32_u24_e32 v124, s16, v154
	v_mul_u32_u24_e32 v126, s16, v155
	s_mov_b64 s[80:81], s[14:15]
	v_mov_b32_e32 v122, v0
	v_lshlrev_b32_e32 v66, 2, v66
	v_mov_b32_e32 v67, v1
	v_lshlrev_b32_e32 v68, 2, v68
	v_mov_b32_e32 v69, v1
	v_lshlrev_b32_e32 v74, 2, v74
	v_mov_b32_e32 v75, v1
	v_lshlrev_b32_e32 v76, 2, v76
	v_mov_b32_e32 v77, v1
	v_lshlrev_b32_e32 v82, 2, v82
	v_mov_b32_e32 v83, v1
	v_lshlrev_b32_e32 v84, 2, v84
	v_mov_b32_e32 v85, v1
	v_lshlrev_b32_e32 v90, 2, v90
	v_mov_b32_e32 v91, v1
	v_lshlrev_b32_e32 v92, 2, v92
	v_mov_b32_e32 v93, v1
	v_lshlrev_b32_e32 v98, 2, v98
	v_mov_b32_e32 v99, v1
	v_lshlrev_b32_e32 v100, 2, v100
	v_mov_b32_e32 v101, v1
	v_lshlrev_b32_e32 v106, 2, v106
	v_mov_b32_e32 v107, v1
	v_lshlrev_b32_e32 v108, 2, v108
	v_mov_b32_e32 v109, v1
	v_lshlrev_b32_e32 v114, 2, v114
	v_mov_b32_e32 v115, v1
	v_lshlrev_b32_e32 v116, 2, v116
	v_mov_b32_e32 v117, v1
	v_lshlrev_b32_e32 v124, 2, v124
	v_mov_b32_e32 v125, v1
	v_lshlrev_b32_e32 v126, 2, v126
	v_mov_b32_e32 v127, v1
	v_add_u32_e32 v66, v122, v66
	v_add_u32_e32 v70, v122, v68
	v_add_u32_e32 v74, v122, v74
	v_add_u32_e32 v78, v122, v76
	v_add_u32_e32 v82, v122, v82
	v_add_u32_e32 v86, v122, v84
	v_add_u32_e32 v90, v122, v90
	v_add_u32_e32 v94, v122, v92
	v_add_u32_e32 v98, v122, v98
	v_add_u32_e32 v102, v122, v100
	v_add_u32_e32 v106, v122, v106
	v_add_u32_e32 v110, v122, v108
	v_add_u32_e32 v114, v122, v114
	v_add_u32_e32 v118, v122, v116
	v_add_u32_e32 v124, v122, v124
	v_add_u32_e32 v126, v122, v126
	global_load_dwordx4 v[66:69], v66, s[80:81] nt
	s_nop 0
	global_load_dwordx4 v[70:73], v70, s[80:81] nt
	s_nop 0
	global_load_dwordx4 v[74:77], v74, s[80:81] nt
	s_nop 0
	global_load_dwordx4 v[78:81], v78, s[80:81] nt
	s_nop 0
	global_load_dwordx4 v[82:85], v82, s[80:81] nt
	s_nop 0
	global_load_dwordx4 v[86:89], v86, s[80:81] nt
	s_nop 0
	global_load_dwordx4 v[90:93], v90, s[80:81] nt
	s_nop 0
	global_load_dwordx4 v[94:97], v94, s[80:81] nt
	s_nop 0
	global_load_dwordx4 v[98:101], v98, s[80:81] nt
	s_nop 0
	global_load_dwordx4 v[102:105], v102, s[80:81] nt
	s_nop 0
	global_load_dwordx4 v[106:109], v106, s[80:81] nt
	s_nop 0
	global_load_dwordx4 v[110:113], v110, s[80:81] nt
	s_nop 0
	global_load_dwordx4 v[114:117], v114, s[80:81] nt
	s_nop 0
	global_load_dwordx4 v[118:121], v118, s[80:81] nt
	s_nop 0
	global_load_dwordx4 v[122:125], v124, s[80:81] nt
	s_nop 0
	global_load_dwordx4 v[126:129], v126, s[80:81] nt
	s_ashr_i32 s14, s30, 31
	s_mul_hi_u32 s15, s30, s51
	s_mul_i32 s14, s14, s51
	s_add_i32 s15, s15, s14
	s_mul_i32 s14, s30, s51
	s_lshl_b64 s[14:15], s[14:15], 1
	s_add_u32 s14, s12, s14
	s_addc_u32 s15, s13, s15
	s_lshl_b64 s[12:13], s[20:21], 1
	s_add_u32 s12, s14, s12
	s_addc_u32 s13, s15, s13
.LBB0_153:
	s_waitcnt vmcnt(0)
	v_cvt_pk_bf16_f32 v174, v6, v2
	v_cvt_pk_bf16_f32 v175, v14, v10
	v_cvt_pk_bf16_f32 v176, v22, v18
	v_cvt_pk_bf16_f32 v177, v30, v26
	v_cvt_pk_bf16_f32 v178, v38, v34
	v_cvt_pk_bf16_f32 v179, v46, v42
	v_cvt_pk_bf16_f32 v180, v54, v50
	v_cvt_pk_bf16_f32 v181, v62, v58
	ds_write_b128 v156, v[174:177]
	ds_write_b128 v157, v[178:181]
	v_cvt_pk_bf16_f32 v174, v7, v3
	v_cvt_pk_bf16_f32 v175, v15, v11
	v_cvt_pk_bf16_f32 v176, v23, v19
	v_cvt_pk_bf16_f32 v177, v31, v27
	v_cvt_pk_bf16_f32 v178, v39, v35
	v_cvt_pk_bf16_f32 v179, v47, v43
	v_cvt_pk_bf16_f32 v180, v55, v51
	v_cvt_pk_bf16_f32 v181, v63, v59
	ds_write_b128 v156, v[174:177] offset:128
	ds_write_b128 v157, v[178:181] offset:128
	v_cvt_pk_bf16_f32 v174, v8, v4
	v_cvt_pk_bf16_f32 v175, v16, v12
	v_cvt_pk_bf16_f32 v176, v24, v20
	v_cvt_pk_bf16_f32 v177, v32, v28
	v_cvt_pk_bf16_f32 v2, v9, v5
	v_cvt_pk_bf16_f32 v3, v17, v13
	v_cvt_pk_bf16_f32 v4, v25, v21
	v_cvt_pk_bf16_f32 v5, v33, v29
	v_cvt_pk_bf16_f32 v178, v40, v36
	v_cvt_pk_bf16_f32 v179, v48, v44
	v_cvt_pk_bf16_f32 v180, v56, v52
	v_cvt_pk_bf16_f32 v181, v64, v60
	ds_write_b128 v156, v[174:177] offset:256
	ds_write_b128 v157, v[178:181] offset:256
	v_cvt_pk_bf16_f32 v6, v41, v37
	v_cvt_pk_bf16_f32 v7, v49, v45
	v_cvt_pk_bf16_f32 v8, v57, v53
	v_cvt_pk_bf16_f32 v9, v65, v61
	ds_write_b128 v156, v[2:5] offset:384
	ds_write_b128 v157, v[6:9] offset:384
	s_waitcnt lgkmcnt(0)
	v_mov_b32_e32 v147, v1
	ds_read_b128 v[2:5], v158
	s_mov_b64 s[82:83], s[0:1]
	v_mov_b32_e32 v10, v146
	v_mad_u64_u32 v[6:7], s[0:1], s48, v130, 0
	v_lshl_add_u32 v12, v6, 1, v10
	ds_read_b128 v[6:9], v159
	s_waitcnt lgkmcnt(1)
	global_store_dwordx4 v12, v[2:5], s[82:83]
	s_addk_i32 s49, 0x300
	v_mov_b64_e32 v[58:59], v[126:127]
	v_mad_u64_u32 v[2:3], s[0:1], s48, v132, 0
	v_lshl_add_u32 v2, v2, 1, v10
	s_waitcnt lgkmcnt(0)
	global_store_dwordx4 v2, v[6:9], s[82:83]
	ds_read_b128 v[2:5], v160
	v_mov_b64_e32 v[62:63], v[122:123]
	v_mad_u64_u32 v[6:7], s[0:1], s48, v134, 0
	v_lshl_add_u32 v12, v6, 1, v10
	ds_read_b128 v[6:9], v161
	s_waitcnt lgkmcnt(1)
	global_store_dwordx4 v12, v[2:5], s[82:83]
	v_mov_b64_e32 v[50:51], v[118:119]
	v_mov_b64_e32 v[54:55], v[114:115]
	v_mad_u64_u32 v[2:3], s[0:1], s48, v136, 0
	v_lshl_add_u32 v2, v2, 1, v10
	s_waitcnt lgkmcnt(0)
	global_store_dwordx4 v2, v[6:9], s[82:83]
	ds_read_b128 v[2:5], v162
	v_mov_b64_e32 v[42:43], v[110:111]
	v_mad_u64_u32 v[6:7], s[0:1], s48, v138, 0
	v_lshl_add_u32 v12, v6, 1, v10
	ds_read_b128 v[6:9], v163
	s_waitcnt lgkmcnt(1)
	global_store_dwordx4 v12, v[2:5], s[82:83]
	v_mov_b64_e32 v[46:47], v[106:107]
	v_mov_b64_e32 v[34:35], v[102:103]
	v_mad_u64_u32 v[2:3], s[0:1], s48, v140, 0
	v_lshl_add_u32 v2, v2, 1, v10
	s_waitcnt lgkmcnt(0)
	global_store_dwordx4 v2, v[6:9], s[82:83]
	ds_read_b128 v[2:5], v164
	v_mov_b64_e32 v[38:39], v[98:99]
	v_mad_u64_u32 v[6:7], s[0:1], s48, v142, 0
	v_lshl_add_u32 v12, v6, 1, v10
	ds_read_b128 v[6:9], v165
	s_waitcnt lgkmcnt(1)
	global_store_dwordx4 v12, v[2:5], s[82:83]
	v_mov_b64_e32 v[26:27], v[94:95]
	v_mov_b64_e32 v[30:31], v[90:91]
	v_mad_u64_u32 v[2:3], s[0:1], s48, v144, 0
	v_lshl_add_u32 v2, v2, 1, v10
	s_waitcnt lgkmcnt(0)
	global_store_dwordx4 v2, v[6:9], s[82:83]
	s_waitcnt lgkmcnt(0)
	v_mov_b64_e32 v[18:19], v[86:87]
	v_mov_b64_e32 v[22:23], v[82:83]
	v_mov_b64_e32 v[10:11], v[78:79]
	v_mov_b64_e32 v[14:15], v[74:75]
	v_mov_b64_e32 v[2:3], v[70:71]
	v_mov_b64_e32 v[6:7], v[66:67]
	s_cmpk_lt_i32 s50, 0x4300
	v_mov_b64_e32 v[60:61], v[128:129]
	v_mov_b64_e32 v[64:65], v[124:125]
	v_mov_b64_e32 v[52:53], v[120:121]
	v_mov_b64_e32 v[56:57], v[116:117]
	v_mov_b64_e32 v[44:45], v[112:113]
	v_mov_b64_e32 v[48:49], v[108:109]
	v_mov_b64_e32 v[36:37], v[104:105]
	v_mov_b64_e32 v[40:41], v[100:101]
	v_mov_b64_e32 v[28:29], v[96:97]
	v_mov_b64_e32 v[32:33], v[92:93]
	v_mov_b64_e32 v[20:21], v[88:89]
	v_mov_b64_e32 v[24:25], v[84:85]
	v_mov_b64_e32 v[12:13], v[80:81]
	v_mov_b64_e32 v[16:17], v[76:77]
	v_mov_b64_e32 v[4:5], v[72:73]
	v_mov_b64_e32 v[8:9], v[68:69]
	s_mov_b64 s[0:1], s[12:13]
	s_mov_b32 s48, s51
	s_cbranch_scc0 .LBB0_183

.LBB0_767:
	v_lshl_add_u32 v188, s76, 7, v221
	v_ashrrev_i32_e32 v189, 31, v188
	v_lshlrev_b64 v[130:131], 2, v[188:189]
	v_lshl_add_u64 v[132:133], s[20:21], 0, v[130:131]
	v_lshl_add_u64 v[134:135], s[44:45], 0, v[130:131]
	v_lshl_add_u64 v[136:137], s[46:47], 0, v[130:131]
	v_lshl_add_u64 v[130:131], s[22:23], 0, v[130:131]
	global_load_dwordx4 v[158:161], v[132:133], off offset:16
	global_load_dwordx4 v[142:145], v[132:133], off
	global_load_dwordx4 v[154:157], v[134:135], off offset:16
	global_load_dwordx4 v[138:141], v[134:135], off
	global_load_dwordx4 v[150:153], v[136:137], off offset:16
	s_nop 0
	global_load_dwordx4 v[134:137], v[136:137], off
	s_nop 0
	global_load_dwordx4 v[146:149], v[130:131], off offset:16
	s_nop 0
	global_load_dwordx4 v[130:133], v[130:131], off
	v_mov_b32_e32 v190, v1
	v_mov_b32_e32 v194, v1
	v_mov_b32_e32 v191, v1
	v_mov_b32_e32 v195, v1
	v_mov_b32_e32 v192, v1
	v_mov_b32_e32 v196, v1
	v_mov_b32_e32 v193, v1
	v_mov_b32_e32 v197, v1
	v_mov_b32_dpp v190, v82 row_shr:1 row_mask:0xf bank_mask:0xf
	v_mov_b32_dpp v194, v86 row_shr:1 row_mask:0xf bank_mask:0xf
	v_mov_b32_dpp v191, v83 row_shr:1 row_mask:0xf bank_mask:0xf
	v_mov_b32_dpp v195, v87 row_shr:1 row_mask:0xf bank_mask:0xf
	v_mov_b32_dpp v192, v84 row_shr:1 row_mask:0xf bank_mask:0xf
	v_mov_b32_dpp v196, v88 row_shr:1 row_mask:0xf bank_mask:0xf
	v_mov_b32_dpp v193, v85 row_shr:1 row_mask:0xf bank_mask:0xf
	v_mov_b32_dpp v197, v89 row_shr:1 row_mask:0xf bank_mask:0xf
	v_cmp_lt_i32_e32 vcc, 14, v218
	s_mov_b64 s[62:63], 0
	s_and_saveexec_b64 s[30:31], vcc
	s_xor_b64 s[64:65], exec, s[30:31]
	s_mov_b64 s[62:63], exec
	v_cvt_pk_bf16_f32 v162, v86, v87
	v_cvt_pk_bf16_f32 v163, v88, v89
	v_cvt_pk_bf16_f32 v164, v82, v83
	v_cvt_pk_bf16_f32 v165, v84, v85
	s_or_saveexec_b64 s[64:65], s[64:65]
	s_lshl_b32 s49, s69, 8
	s_add_i32 s49, s49, s35
	v_ashrrev_i32_e32 v184, 2, v188
	s_ashr_i32 s30, s49, 6
	v_ashrrev_i32_e32 v185, 31, v184
	v_mad_i64_i32 v[166:167], s[72:73], s30, v235, v[184:185]
	v_lshlrev_b64 v[186:187], 4, v[166:167]
	v_mov_b64_e32 v[198:199], 0x72c00000
	s_xor_b64 exec, exec, s[64:65]
	s_cbranch_execz .LBB0_773
	v_cmp_eq_u32_e32 vcc, 0, v218
	s_mov_b64 s[74:75], s[62:63]
	s_and_saveexec_b64 s[72:73], vcc
	s_cbranch_execz .LBB0_772
	v_cvt_pk_bf16_f32 v170, v94, v95
	v_cvt_pk_bf16_f32 v171, v96, v97
	v_cvt_pk_bf16_f32 v172, v90, v91
	v_cvt_pk_bf16_f32 v173, v92, v93
	v_cvt_pk_bf16_f32 v162, v78, v79
	v_cvt_pk_bf16_f32 v163, v80, v81
	v_cvt_pk_bf16_f32 v164, v74, v75
	v_cvt_pk_bf16_f32 v165, v76, v77
	v_lshl_add_u64 v[166:167], s[40:41], 0, v[186:187]
	s_or_b64 s[74:75], s[62:63], exec
	v_subrev_u32_e32 v166, s12, v166
	global_store_dwordx4 v166, v[170:173], s[12:13]

.LBB0_773:
	s_or_b64 exec, exec, s[64:65]
	s_and_saveexec_b64 s[64:65], s[62:63]
	s_cbranch_execz .LBB0_775
	v_lshl_add_u64 v[166:167], s[12:13], 0, v[198:199]
	v_lshl_add_u64 v[166:167], v[166:167], 0, v[186:187]
	v_subrev_u32_e32 v166, s12, v166
	global_store_dwordx4 v166, v[162:165], s[12:13]
.LBB0_775:
	s_or_b64 exec, exec, s[64:65]
	v_mov_b32_e32 v198, v1
	v_mov_b32_e32 v202, v1
	v_mov_b32_e32 v199, v1
	v_mov_b32_e32 v203, v1
	v_mov_b32_e32 v200, v1
	v_mov_b32_e32 v204, v1
	v_mov_b32_e32 v201, v1
	v_mov_b32_e32 v205, v1
	s_mul_hi_i32 s73, s30, 0x580
	s_mul_i32 s72, s30, 0x580
	v_mov_b32_dpp v198, v114 row_shr:1 row_mask:0xf bank_mask:0xf
	v_mov_b32_dpp v202, v118 row_shr:1 row_mask:0xf bank_mask:0xf
	v_mov_b32_dpp v199, v115 row_shr:1 row_mask:0xf bank_mask:0xf
	v_mov_b32_dpp v203, v119 row_shr:1 row_mask:0xf bank_mask:0xf
	v_mov_b32_dpp v200, v116 row_shr:1 row_mask:0xf bank_mask:0xf
	v_mov_b32_dpp v204, v120 row_shr:1 row_mask:0xf bank_mask:0xf
	v_mov_b32_dpp v201, v117 row_shr:1 row_mask:0xf bank_mask:0xf
	v_mov_b32_dpp v205, v121 row_shr:1 row_mask:0xf bank_mask:0xf
	v_cmp_lt_i32_e32 vcc, 14, v218
	s_mov_b64 s[62:63], 0
	s_and_saveexec_b64 s[30:31], vcc
	s_xor_b64 s[64:65], exec, s[30:31]
	s_mov_b64 s[62:63], exec
	v_cvt_pk_bf16_f32 v162, v118, v119
	v_cvt_pk_bf16_f32 v163, v120, v121
	v_cvt_pk_bf16_f32 v164, v114, v115
	v_cvt_pk_bf16_f32 v165, v116, v117
	s_or_saveexec_b64 s[64:65], s[64:65]
	v_or_b32_e32 v186, 1, v184
	v_ashrrev_i32_e32 v187, 31, v186
	v_lshl_add_u64 v[166:167], s[72:73], 0, v[186:187]
	v_lshlrev_b64 v[206:207], 4, v[166:167]
	v_mov_b64_e32 v[208:209], 0x72c00000
	s_xor_b64 exec, exec, s[64:65]
	s_cbranch_execz .LBB0_781
	v_cmp_eq_u32_e32 vcc, 0, v218
	s_mov_b64 s[74:75], s[62:63]
	s_and_saveexec_b64 s[72:73], vcc
	s_cbranch_execz .LBB0_780
	v_cvt_pk_bf16_f32 v170, v126, v127
	v_cvt_pk_bf16_f32 v171, v128, v129
	v_cvt_pk_bf16_f32 v172, v122, v123
	v_cvt_pk_bf16_f32 v173, v124, v125
	v_cvt_pk_bf16_f32 v162, v110, v111
	v_cvt_pk_bf16_f32 v163, v112, v113
	v_cvt_pk_bf16_f32 v164, v106, v107
	v_cvt_pk_bf16_f32 v165, v108, v109
	v_lshl_add_u64 v[166:167], s[40:41], 0, v[206:207]
	s_or_b64 s[74:75], s[62:63], exec
	v_subrev_u32_e32 v166, s12, v166
	global_store_dwordx4 v166, v[170:173], s[12:13]

.LBB0_781:
	s_or_b64 exec, exec, s[64:65]
	s_and_saveexec_b64 s[64:65], s[62:63]
	s_cbranch_execz .LBB0_783
	v_lshl_add_u64 v[166:167], s[12:13], 0, v[208:209]
	v_lshl_add_u64 v[166:167], v[166:167], 0, v[206:207]
	v_subrev_u32_e32 v166, s12, v166
	global_store_dwordx4 v166, v[162:165], s[12:13]
.LBB0_783:
	s_or_b64 exec, exec, s[64:65]
	s_waitcnt vmcnt(4)
	v_pk_mul_f32 v[160:161], v[160:161], s[34:35] op_sel_hi:[1,0]
	v_pk_mul_f32 v[158:159], v[158:159], s[34:35] op_sel_hi:[1,0]
	v_pk_mul_f32 v[148:149], v[148:149], s[34:35] op_sel_hi:[1,0]
	v_pk_mul_f32 v[146:147], v[146:147], s[34:35] op_sel_hi:[1,0]
	v_pk_mul_f32 v[156:157], v[156:157], s[34:35] op_sel_hi:[1,0]
	v_pk_mul_f32 v[154:155], v[154:155], s[34:35] op_sel_hi:[1,0]
	v_pk_fma_f32 v[162:163], v[160:161], v[204:205], v[148:149]
	v_pk_fma_f32 v[164:165], v[158:159], v[202:203], v[146:147]
	v_pk_mul_f32 v[152:153], v[152:153], s[34:35] op_sel_hi:[1,0]
	v_pk_mul_f32 v[150:151], v[150:151], s[34:35] op_sel_hi:[1,0]
	v_pk_fma_f32 v[164:165], v[154:155], v[198:199], v[164:165]
	v_pk_fma_f32 v[162:163], v[156:157], v[200:201], v[162:163]
	v_pk_fma_f32 v[166:167], v[160:161], v[200:201], v[148:149]
	v_pk_fma_f32 v[170:171], v[158:159], v[198:199], v[146:147]
	v_pk_fma_f32 v[162:163], v[128:129], v[152:153], v[162:163]
	v_pk_fma_f32 v[164:165], v[126:127], v[150:151], v[164:165]
	v_pk_fma_f32 v[170:171], v[126:127], v[154:155], v[170:171]
	v_pk_fma_f32 v[166:167], v[128:129], v[156:157], v[166:167]
	v_pk_fma_f32 v[128:129], v[128:129], v[160:161], v[148:149]
	v_pk_fma_f32 v[126:127], v[126:127], v[158:159], v[146:147]
	v_pk_fma_f32 v[166:167], v[124:125], v[152:153], v[166:167]
	v_pk_fma_f32 v[170:171], v[122:123], v[150:151], v[170:171]
	v_pk_fma_f32 v[126:127], v[122:123], v[154:155], v[126:127]
	v_pk_fma_f32 v[128:129], v[124:125], v[156:157], v[128:129]
	v_pk_fma_f32 v[124:125], v[124:125], v[160:161], v[148:149]
	v_pk_fma_f32 v[122:123], v[122:123], v[158:159], v[146:147]
	v_pk_fma_f32 v[128:129], v[120:121], v[152:153], v[128:129]
	v_pk_fma_f32 v[126:127], v[118:119], v[150:151], v[126:127]
	v_pk_fma_f32 v[118:119], v[118:119], v[154:155], v[122:123]
	v_pk_fma_f32 v[120:121], v[120:121], v[156:157], v[124:125]
	v_exp_f32_e64 v122, -v164
	v_exp_f32_e64 v124, -v162
	v_exp_f32_e64 v125, -v163
	v_exp_f32_e64 v123, -v165
	v_pk_fma_f32 v[120:121], v[116:117], v[152:153], v[120:121]
	v_pk_fma_f32 v[118:119], v[114:115], v[150:151], v[118:119]
	v_pk_fma_f32 v[114:115], v[124:125], s[34:35], s[34:35] op_sel_hi:[1,0,0]
	v_pk_fma_f32 v[116:117], v[122:123], s[34:35], s[34:35] op_sel_hi:[1,0,0]
	v_rcp_f32_e32 v114, v114
	v_rcp_f32_e32 v116, v116
	v_rcp_f32_e32 v117, v117
	v_rcp_f32_e32 v115, v115
	v_exp_f32_e64 v122, -v170
	v_exp_f32_e64 v124, -v166
	v_exp_f32_e64 v125, -v167
	v_exp_f32_e64 v123, -v171
	v_pk_mul_f32 v[110:111], v[110:111], v[164:165]
	v_pk_mul_f32 v[112:113], v[112:113], v[162:163]
	v_pk_mul_f32 v[116:117], v[110:111], v[116:117]
	v_pk_mul_f32 v[114:115], v[112:113], v[114:115]
	v_pk_fma_f32 v[110:111], v[124:125], s[34:35], s[34:35] op_sel_hi:[1,0,0]
	v_pk_fma_f32 v[112:113], v[122:123], s[34:35], s[34:35] op_sel_hi:[1,0,0]
	v_rcp_f32_e32 v110, v110
	v_rcp_f32_e32 v112, v112
	v_rcp_f32_e32 v113, v113
	v_rcp_f32_e32 v111, v111
	v_exp_f32_e64 v122, -v126
	v_exp_f32_e64 v124, -v128
	v_exp_f32_e64 v125, -v129
	v_exp_f32_e64 v123, -v127
	v_pk_mul_f32 v[106:107], v[106:107], v[170:171]
	v_pk_mul_f32 v[108:109], v[108:109], v[166:167]
	v_pk_mul_f32 v[164:165], v[106:107], v[112:113]
	v_pk_mul_f32 v[162:163], v[108:109], v[110:111]
	v_pk_fma_f32 v[106:107], v[124:125], s[34:35], s[34:35] op_sel_hi:[1,0,0]
	v_pk_fma_f32 v[108:109], v[122:123], s[34:35], s[34:35] op_sel_hi:[1,0,0]
	v_rcp_f32_e32 v106, v106
	v_rcp_f32_e32 v108, v108
	v_rcp_f32_e32 v109, v109
	v_rcp_f32_e32 v107, v107
	v_exp_f32_e64 v110, -v118
	v_exp_f32_e64 v112, -v120
	v_exp_f32_e64 v113, -v121
	v_exp_f32_e64 v111, -v119
	v_pk_mul_f32 v[102:103], v[102:103], v[126:127]
	v_pk_mul_f32 v[104:105], v[104:105], v[128:129]
	v_pk_mul_f32 v[124:125], v[102:103], v[108:109]
	v_pk_mul_f32 v[122:123], v[104:105], v[106:107]
	v_pk_fma_f32 v[102:103], v[112:113], s[34:35], s[34:35] op_sel_hi:[1,0,0]
	v_pk_fma_f32 v[104:105], v[110:111], s[34:35], s[34:35] op_sel_hi:[1,0,0]
	v_rcp_f32_e32 v102, v102
	v_rcp_f32_e32 v104, v104
	v_rcp_f32_e32 v103, v103
	v_rcp_f32_e32 v105, v105
	v_pk_mul_f32 v[98:99], v[98:99], v[118:119]
	v_pk_mul_f32 v[100:101], v[100:101], v[120:121]
	v_pk_mul_f32 v[112:113], v[132:133], s[34:35] op_sel_hi:[1,0]
	v_pk_mul_f32 v[118:119], v[100:101], v[102:103]
	v_pk_mul_f32 v[120:121], v[98:99], v[104:105]
	v_pk_mul_f32 v[100:101], v[144:145], s[34:35] op_sel_hi:[1,0]
	v_pk_mul_f32 v[98:99], v[142:143], s[34:35] op_sel_hi:[1,0]
	v_pk_mul_f32 v[110:111], v[130:131], s[34:35] op_sel_hi:[1,0]
	v_pk_mul_f32 v[104:105], v[140:141], s[34:35] op_sel_hi:[1,0]
	v_pk_mul_f32 v[102:103], v[138:139], s[34:35] op_sel_hi:[1,0]
	v_pk_fma_f32 v[126:127], v[100:101], v[196:197], v[112:113]
	v_pk_fma_f32 v[128:129], v[98:99], v[194:195], v[110:111]
	v_pk_mul_f32 v[108:109], v[136:137], s[34:35] op_sel_hi:[1,0]
	v_pk_mul_f32 v[106:107], v[134:135], s[34:35] op_sel_hi:[1,0]
	v_pk_fma_f32 v[128:129], v[102:103], v[190:191], v[128:129]
	v_pk_fma_f32 v[126:127], v[104:105], v[192:193], v[126:127]
	v_pk_fma_f32 v[130:131], v[100:101], v[192:193], v[112:113]
	v_pk_fma_f32 v[132:133], v[98:99], v[190:191], v[110:111]
	v_pk_fma_f32 v[126:127], v[96:97], v[108:109], v[126:127]
	v_pk_fma_f32 v[128:129], v[94:95], v[106:107], v[128:129]
	v_pk_fma_f32 v[132:133], v[94:95], v[102:103], v[132:133]
	v_pk_fma_f32 v[130:131], v[96:97], v[104:105], v[130:131]
	v_pk_fma_f32 v[96:97], v[96:97], v[100:101], v[112:113]
	v_pk_fma_f32 v[94:95], v[94:95], v[98:99], v[110:111]
	v_pk_fma_f32 v[130:131], v[92:93], v[108:109], v[130:131]
	v_pk_fma_f32 v[132:133], v[90:91], v[106:107], v[132:133]
	v_pk_fma_f32 v[96:97], v[92:93], v[104:105], v[96:97]
	v_pk_fma_f32 v[94:95], v[90:91], v[102:103], v[94:95]
	v_pk_fma_f32 v[92:93], v[92:93], v[100:101], v[112:113]
	v_pk_fma_f32 v[90:91], v[90:91], v[98:99], v[110:111]
	v_pk_fma_f32 v[96:97], v[88:89], v[108:109], v[96:97]
	v_pk_fma_f32 v[94:95], v[86:87], v[106:107], v[94:95]
	v_pk_fma_f32 v[88:89], v[88:89], v[104:105], v[92:93]
	v_pk_fma_f32 v[86:87], v[86:87], v[102:103], v[90:91]
	v_exp_f32_e64 v90, -v128
	v_exp_f32_e64 v92, -v126
	v_exp_f32_e64 v93, -v127
	v_exp_f32_e64 v91, -v129
	v_pk_fma_f32 v[84:85], v[84:85], v[108:109], v[88:89]
	v_pk_fma_f32 v[82:83], v[82:83], v[106:107], v[86:87]
	v_pk_fma_f32 v[86:87], v[92:93], s[34:35], s[34:35] op_sel_hi:[1,0,0]
	v_pk_fma_f32 v[88:89], v[90:91], s[34:35], s[34:35] op_sel_hi:[1,0,0]
	v_rcp_f32_e32 v86, v86
	v_rcp_f32_e32 v88, v88
	v_rcp_f32_e32 v89, v89
	v_rcp_f32_e32 v87, v87
	v_exp_f32_e64 v90, -v132
	v_exp_f32_e64 v92, -v130
	v_exp_f32_e64 v93, -v131
	v_exp_f32_e64 v91, -v133
	v_pk_mul_f32 v[78:79], v[78:79], v[128:129]
	v_pk_mul_f32 v[80:81], v[80:81], v[126:127]
	v_pk_mul_f32 v[78:79], v[78:79], v[88:89]
	v_pk_mul_f32 v[80:81], v[80:81], v[86:87]
	v_pk_fma_f32 v[86:87], v[92:93], s[34:35], s[34:35] op_sel_hi:[1,0,0]
	v_pk_fma_f32 v[88:89], v[90:91], s[34:35], s[34:35] op_sel_hi:[1,0,0]
	v_rcp_f32_e32 v86, v86
	v_rcp_f32_e32 v88, v88
	v_rcp_f32_e32 v89, v89
	v_rcp_f32_e32 v87, v87
	v_exp_f32_e64 v90, -v94
	v_exp_f32_e64 v92, -v96
	v_exp_f32_e64 v93, -v97
	v_exp_f32_e64 v91, -v95
	v_pk_mul_f32 v[74:75], v[74:75], v[132:133]
	v_pk_mul_f32 v[76:77], v[76:77], v[130:131]
	v_pk_mul_f32 v[74:75], v[74:75], v[88:89]
	v_pk_mul_f32 v[76:77], v[76:77], v[86:87]
	v_pk_fma_f32 v[86:87], v[92:93], s[34:35], s[34:35] op_sel_hi:[1,0,0]
	v_pk_fma_f32 v[88:89], v[90:91], s[34:35], s[34:35] op_sel_hi:[1,0,0]
	v_rcp_f32_e32 v86, v86
	v_rcp_f32_e32 v88, v88
	v_rcp_f32_e32 v89, v89
	v_rcp_f32_e32 v87, v87
	v_exp_f32_e64 v90, -v82
	v_exp_f32_e64 v91, -v83
	v_exp_f32_e64 v92, -v84
	v_exp_f32_e64 v93, -v85
	v_pk_mul_f32 v[72:73], v[72:73], v[96:97]
	v_pk_mul_f32 v[70:71], v[70:71], v[94:95]
	v_pk_mul_f32 v[72:73], v[72:73], v[86:87]
	v_pk_mul_f32 v[86:87], v[70:71], v[88:89]
	v_pk_fma_f32 v[88:89], v[90:91], s[34:35], s[34:35] op_sel_hi:[1,0,0]
	v_pk_fma_f32 v[70:71], v[92:93], s[34:35], s[34:35] op_sel_hi:[1,0,0]
	v_rcp_f32_e32 v88, v88
	v_rcp_f32_e32 v89, v89
	v_rcp_f32_e32 v70, v70
	v_rcp_f32_e32 v71, v71
	v_pk_mul_f32 v[66:67], v[66:67], v[82:83]
	v_pk_mul_f32 v[68:69], v[68:69], v[84:85]
	v_pk_mul_f32 v[84:85], v[66:67], v[88:89]
	v_or_b32_e32 v88, s49, v219
	v_cvt_pk_bf16_f32 v66, v78, v79
	v_mov_b64_e32 v[78:79], s[16:17]
	s_movk_i32 s51, 0x2c00
	v_pk_mul_f32 v[82:83], v[68:69], v[70:71]
	v_cvt_pk_bf16_f32 v67, v80, v81
	v_mad_i64_i32 v[80:81], s[30:31], v88, s51, v[78:79]
	v_lshlrev_b64 v[70:71], 1, v[188:189]
	v_cvt_pk_bf16_f32 v68, v116, v117
	v_cvt_pk_bf16_f32 v69, v114, v115
	v_lshl_add_u64 v[80:81], v[80:81], 0, v[70:71]
	v_subrev_u32_e32 v80, s12, v80
	global_store_dwordx4 v80, v[66:69], s[12:13]
	v_cmp_lt_i32_e32 vcc, 14, v218
	s_mov_b64 s[62:63], 0
	v_cvt_pk_bf16_f32 v66, v74, v75
	v_or_b32_e32 v74, 1, v88
	v_mad_i64_i32 v[74:75], s[30:31], v74, s51, v[78:79]
	v_cvt_pk_bf16_f32 v67, v76, v77
	v_cvt_pk_bf16_f32 v68, v164, v165
	v_cvt_pk_bf16_f32 v69, v162, v163
	v_lshl_add_u64 v[74:75], v[74:75], 0, v[70:71]
	v_subrev_u32_e32 v74, s12, v74
	global_store_dwordx4 v74, v[66:69], s[12:13]
	v_mov_b32_e32 v74, v1
	v_mov_b32_e32 v75, v1
	v_cvt_pk_bf16_f32 v67, v72, v73
	v_or_b32_e32 v72, 2, v88
	v_mad_i64_i32 v[72:73], s[30:31], v72, s51, v[78:79]
	v_cvt_pk_bf16_f32 v66, v86, v87
	v_cvt_pk_bf16_f32 v68, v124, v125
	v_cvt_pk_bf16_f32 v69, v122, v123
	v_lshl_add_u64 v[72:73], v[72:73], 0, v[70:71]
	v_subrev_u32_e32 v72, s12, v72
	global_store_dwordx4 v72, v[66:69], s[12:13]
	v_or_b32_e32 v72, 3, v88
	v_mad_i64_i32 v[72:73], s[30:31], v72, s51, v[78:79]
	v_cvt_pk_bf16_f32 v66, v84, v85
	v_cvt_pk_bf16_f32 v67, v82, v83
	v_cvt_pk_bf16_f32 v68, v120, v121
	v_cvt_pk_bf16_f32 v69, v118, v119
	v_lshl_add_u64 v[72:73], v[72:73], 0, v[70:71]
	v_subrev_u32_e32 v72, s12, v72
	global_store_dwordx4 v72, v[66:69], s[12:13]
	v_mov_b32_e32 v72, v1
	v_mov_b32_e32 v73, v1
	v_mov_b32_e32 v76, v1
	v_mov_b32_e32 v78, v1
	v_mov_b32_e32 v77, v1
	v_mov_b32_e32 v79, v1
	v_mov_b32_dpp v72, v30 row_shr:1 row_mask:0xf bank_mask:0xf
	v_mov_b32_dpp v74, v26 row_shr:1 row_mask:0xf bank_mask:0xf
	v_mov_b32_dpp v73, v31 row_shr:1 row_mask:0xf bank_mask:0xf
	v_mov_b32_dpp v75, v27 row_shr:1 row_mask:0xf bank_mask:0xf
	v_mov_b32_dpp v76, v32 row_shr:1 row_mask:0xf bank_mask:0xf
	v_mov_b32_dpp v78, v28 row_shr:1 row_mask:0xf bank_mask:0xf
	v_mov_b32_dpp v77, v33 row_shr:1 row_mask:0xf bank_mask:0xf
	v_mov_b32_dpp v79, v29 row_shr:1 row_mask:0xf bank_mask:0xf
	s_and_saveexec_b64 s[30:31], vcc
	s_xor_b64 s[64:65], exec, s[30:31]
	s_mov_b64 s[62:63], exec
	v_cvt_pk_bf16_f32 v66, v26, v27
	v_cvt_pk_bf16_f32 v67, v28, v29
	v_cvt_pk_bf16_f32 v68, v30, v31
	v_cvt_pk_bf16_f32 v69, v32, v33
	s_or_saveexec_b64 s[64:65], s[64:65]
	s_addk_i32 s49, 0x80
	s_ashr_i32 s30, s49, 6
	v_mad_i64_i32 v[80:81], s[72:73], s30, v235, v[184:185]
	v_lshlrev_b64 v[80:81], 4, v[80:81]
	v_mov_b64_e32 v[82:83], 0x72c00000
	s_xor_b64 exec, exec, s[64:65]
	s_cbranch_execz .LBB0_789
	v_cmp_eq_u32_e32 vcc, 0, v218
	s_mov_b64 s[74:75], s[62:63]
	s_and_saveexec_b64 s[72:73], vcc
	s_cbranch_execz .LBB0_788
	v_cvt_pk_bf16_f32 v82, v10, v11
	v_cvt_pk_bf16_f32 v83, v12, v13
	v_cvt_pk_bf16_f32 v84, v18, v19
	v_cvt_pk_bf16_f32 v85, v20, v21
	v_cvt_pk_bf16_f32 v66, v2, v3
	v_cvt_pk_bf16_f32 v67, v4, v5
	v_cvt_pk_bf16_f32 v68, v6, v7
	v_cvt_pk_bf16_f32 v69, v8, v9
	v_lshl_add_u64 v[86:87], s[40:41], 0, v[80:81]
	s_or_b64 s[74:75], s[62:63], exec
	v_subrev_u32_e32 v86, s12, v86
	global_store_dwordx4 v86, v[82:85], s[12:13]

.LBB0_789:
	s_or_b64 exec, exec, s[64:65]
	s_and_saveexec_b64 s[64:65], s[62:63]
	s_cbranch_execz .LBB0_791
	v_lshl_add_u64 v[82:83], s[12:13], 0, v[82:83]
	v_lshl_add_u64 v[80:81], v[82:83], 0, v[80:81]
	v_subrev_u32_e32 v80, s12, v80
	global_store_dwordx4 v80, v[66:69], s[12:13]

.LBB0_799:
	s_or_b64 exec, exec, s[64:65]
	s_nop 0
	v_pk_fma_f32 v[66:67], v[52:53], v[160:161], v[148:149]
	v_pk_fma_f32 v[68:69], v[50:51], v[158:159], v[146:147]
	v_pk_fma_f32 v[66:67], v[60:61], v[156:157], v[66:67]
	v_pk_fma_f32 v[68:69], v[58:59], v[154:155], v[68:69]
	v_pk_fma_f32 v[64:65], v[64:65], v[152:153], v[66:67]
	v_pk_fma_f32 v[62:63], v[62:63], v[150:151], v[68:69]
	v_exp_f32_e64 v68, -v64
	v_exp_f32_e64 v66, -v62
	v_exp_f32_e64 v69, -v65
	v_exp_f32_e64 v67, -v63
	v_pk_mul_f32 v[56:57], v[56:57], v[64:65]
	v_pk_mul_f32 v[62:63], v[54:55], v[62:63]
	v_pk_fma_f32 v[54:55], v[68:69], s[34:35], s[34:35] op_sel_hi:[1,0,0]
	v_pk_fma_f32 v[64:65], v[66:67], s[34:35], s[34:35] op_sel_hi:[1,0,0]
	v_pk_fma_f32 v[66:67], v[44:45], v[160:161], v[148:149]
	v_pk_fma_f32 v[68:69], v[42:43], v[158:159], v[146:147]
	v_pk_fma_f32 v[66:67], v[52:53], v[156:157], v[66:67]
	v_pk_fma_f32 v[68:69], v[50:51], v[154:155], v[68:69]
	v_pk_fma_f32 v[60:61], v[60:61], v[152:153], v[66:67]
	v_pk_fma_f32 v[58:59], v[58:59], v[150:151], v[68:69]
	v_rcp_f32_e32 v64, v64
	v_rcp_f32_e32 v65, v65
	v_rcp_f32_e32 v54, v54
	v_rcp_f32_e32 v55, v55
	v_exp_f32_e64 v66, -v58
	v_exp_f32_e64 v68, -v60
	v_exp_f32_e64 v69, -v61
	v_exp_f32_e64 v67, -v59
	v_pk_mul_f32 v[54:55], v[56:57], v[54:55]
	v_pk_mul_f32 v[56:57], v[62:63], v[64:65]
	v_pk_fma_f32 v[62:63], v[68:69], s[34:35], s[34:35] op_sel_hi:[1,0,0]
	v_pk_fma_f32 v[64:65], v[66:67], s[34:35], s[34:35] op_sel_hi:[1,0,0]
	v_rcp_f32_e32 v62, v62
	v_rcp_f32_e32 v64, v64
	v_rcp_f32_e32 v63, v63
	v_rcp_f32_e32 v65, v65
	v_pk_mul_f32 v[48:49], v[48:49], v[60:61]
	v_pk_mul_f32 v[58:59], v[46:47], v[58:59]
	v_pk_fma_f32 v[60:61], v[158:159], v[80:81], v[146:147]
	v_pk_mul_f32 v[46:47], v[48:49], v[62:63]
	v_pk_mul_f32 v[48:49], v[58:59], v[64:65]
	v_pk_fma_f32 v[58:59], v[160:161], v[84:85], v[148:149]
	v_pk_fma_f32 v[60:61], v[42:43], v[154:155], v[60:61]
	v_pk_fma_f32 v[58:59], v[44:45], v[156:157], v[58:59]
	v_pk_fma_f32 v[50:51], v[50:51], v[150:151], v[60:61]
	v_pk_fma_f32 v[52:53], v[52:53], v[152:153], v[58:59]
	v_exp_f32_e64 v58, -v50
	v_exp_f32_e64 v59, -v51
	v_exp_f32_e64 v60, -v52
	v_exp_f32_e64 v61, -v53
	v_pk_mul_f32 v[40:41], v[40:41], v[52:53]
	v_pk_fma_f32 v[52:53], v[58:59], s[34:35], s[34:35] op_sel_hi:[1,0,0]
	v_pk_fma_f32 v[58:59], v[160:161], v[86:87], v[148:149]
	v_pk_mul_f32 v[38:39], v[38:39], v[50:51]
	v_pk_fma_f32 v[50:51], v[60:61], s[34:35], s[34:35] op_sel_hi:[1,0,0]
	v_pk_fma_f32 v[60:61], v[158:159], v[82:83], v[146:147]
	v_pk_fma_f32 v[58:59], v[156:157], v[84:85], v[58:59]
	v_pk_fma_f32 v[60:61], v[154:155], v[80:81], v[60:61]
	v_pk_fma_f32 v[44:45], v[44:45], v[152:153], v[58:59]
	v_pk_fma_f32 v[42:43], v[42:43], v[150:151], v[60:61]
	v_exp_f32_e64 v60, -v44
	v_exp_f32_e64 v61, -v45
	v_pk_mul_f32 v[36:37], v[36:37], v[44:45]
	v_pk_fma_f32 v[44:45], v[18:19], v[98:99], v[110:111]
	v_exp_f32_e64 v58, -v42
	v_exp_f32_e64 v59, -v43
	v_pk_mul_f32 v[34:35], v[34:35], v[42:43]
	v_pk_fma_f32 v[42:43], v[20:21], v[100:101], v[112:113]
	v_pk_fma_f32 v[44:45], v[26:27], v[102:103], v[44:45]
	v_pk_fma_f32 v[42:43], v[28:29], v[104:105], v[42:43]
	v_pk_fma_f32 v[30:31], v[30:31], v[106:107], v[44:45]
	v_pk_fma_f32 v[32:33], v[32:33], v[108:109], v[42:43]
	v_exp_f32_e64 v42, -v30
	v_exp_f32_e64 v43, -v31
	v_exp_f32_e64 v44, -v32
	v_exp_f32_e64 v45, -v33
	v_pk_mul_f32 v[24:25], v[24:25], v[32:33]
	v_pk_fma_f32 v[32:33], v[42:43], s[34:35], s[34:35] op_sel_hi:[1,0,0]
	v_pk_fma_f32 v[42:43], v[12:13], v[100:101], v[112:113]
	v_pk_mul_f32 v[22:23], v[22:23], v[30:31]
	v_pk_fma_f32 v[30:31], v[44:45], s[34:35], s[34:35] op_sel_hi:[1,0,0]
	v_pk_fma_f32 v[44:45], v[10:11], v[98:99], v[110:111]
	v_pk_fma_f32 v[42:43], v[20:21], v[104:105], v[42:43]
	v_pk_fma_f32 v[44:45], v[18:19], v[102:103], v[44:45]
	v_pk_fma_f32 v[28:29], v[28:29], v[108:109], v[42:43]
	v_pk_fma_f32 v[26:27], v[26:27], v[106:107], v[44:45]
	v_exp_f32_e64 v44, -v28
	v_exp_f32_e64 v45, -v29
	v_pk_mul_f32 v[16:17], v[16:17], v[28:29]
	v_pk_fma_f32 v[28:29], v[98:99], v[72:73], v[110:111]
	v_exp_f32_e64 v42, -v26
	v_exp_f32_e64 v43, -v27
	v_pk_mul_f32 v[14:15], v[14:15], v[26:27]
	v_pk_fma_f32 v[26:27], v[100:101], v[76:77], v[112:113]
	v_pk_fma_f32 v[28:29], v[10:11], v[102:103], v[28:29]
	v_pk_fma_f32 v[26:27], v[12:13], v[104:105], v[26:27]
	v_pk_fma_f32 v[18:19], v[18:19], v[106:107], v[28:29]
	v_pk_fma_f32 v[20:21], v[20:21], v[108:109], v[26:27]
	v_exp_f32_e64 v26, -v18
	v_exp_f32_e64 v27, -v19
	v_exp_f32_e64 v28, -v20
	v_exp_f32_e64 v29, -v21
	v_pk_mul_f32 v[8:9], v[8:9], v[20:21]
	v_pk_fma_f32 v[20:21], v[26:27], s[34:35], s[34:35] op_sel_hi:[1,0,0]
	v_pk_fma_f32 v[26:27], v[100:101], v[78:79], v[112:113]
	v_pk_mul_f32 v[6:7], v[6:7], v[18:19]
	v_pk_fma_f32 v[18:19], v[28:29], s[34:35], s[34:35] op_sel_hi:[1,0,0]
	v_pk_fma_f32 v[28:29], v[98:99], v[74:75], v[110:111]
	v_pk_fma_f32 v[26:27], v[104:105], v[76:77], v[26:27]
	v_pk_fma_f32 v[28:29], v[102:103], v[72:73], v[28:29]
	v_pk_fma_f32 v[12:13], v[12:13], v[108:109], v[26:27]
	v_rcp_f32_e32 v18, v18
	v_rcp_f32_e32 v19, v19
	v_pk_fma_f32 v[10:11], v[10:11], v[106:107], v[28:29]
	v_exp_f32_e64 v28, -v12
	v_exp_f32_e64 v29, -v13
	v_rcp_f32_e32 v52, v52
	v_rcp_f32_e32 v53, v53
	v_rcp_f32_e32 v50, v50
	v_rcp_f32_e32 v51, v51
	v_rcp_f32_e32 v20, v20
	v_rcp_f32_e32 v21, v21
	v_exp_f32_e64 v26, -v10
	v_exp_f32_e64 v27, -v11
	v_pk_mul_f32 v[8:9], v[8:9], v[18:19]
	v_pk_fma_f32 v[18:19], v[28:29], s[34:35], s[34:35] op_sel_hi:[1,0,0]
	v_pk_mul_f32 v[40:41], v[40:41], v[50:51]
	v_pk_mul_f32 v[38:39], v[38:39], v[52:53]
	v_pk_fma_f32 v[50:51], v[60:61], s[34:35], s[34:35] op_sel_hi:[1,0,0]
	v_pk_fma_f32 v[52:53], v[58:59], s[34:35], s[34:35] op_sel_hi:[1,0,0]
	v_pk_mul_f32 v[6:7], v[6:7], v[20:21]
	v_pk_fma_f32 v[20:21], v[26:27], s[34:35], s[34:35] op_sel_hi:[1,0,0]
	v_rcp_f32_e32 v18, v18
	v_rcp_f32_e32 v19, v19
	v_rcp_f32_e32 v52, v52
	v_rcp_f32_e32 v50, v50
	v_rcp_f32_e32 v51, v51
	v_rcp_f32_e32 v53, v53
	v_rcp_f32_e32 v20, v20
	v_rcp_f32_e32 v21, v21
	v_rcp_f32_e32 v32, v32
	v_rcp_f32_e32 v33, v33
	v_rcp_f32_e32 v30, v30
	v_rcp_f32_e32 v31, v31
	v_pk_mul_f32 v[4:5], v[4:5], v[12:13]
	v_pk_mul_f32 v[2:3], v[2:3], v[10:11]
	v_pk_mul_f32 v[4:5], v[4:5], v[18:19]
	v_or_b32_e32 v18, s49, v219
	v_mov_b64_e32 v[10:11], s[16:17]
	s_movk_i32 s49, 0x2c00
	v_pk_mul_f32 v[36:37], v[36:37], v[50:51]
	v_pk_mul_f32 v[34:35], v[34:35], v[52:53]
	v_pk_mul_f32 v[2:3], v[2:3], v[20:21]
	v_mad_i64_i32 v[12:13], s[30:31], v18, s49, v[10:11]
	v_pk_mul_f32 v[24:25], v[24:25], v[30:31]
	v_pk_mul_f32 v[22:23], v[22:23], v[32:33]
	v_pk_fma_f32 v[30:31], v[44:45], s[34:35], s[34:35] op_sel_hi:[1,0,0]
	v_pk_fma_f32 v[32:33], v[42:43], s[34:35], s[34:35] op_sel_hi:[1,0,0]
	v_cvt_pk_bf16_f32 v2, v2, v3
	v_cvt_pk_bf16_f32 v3, v4, v5
	v_cvt_pk_bf16_f32 v4, v34, v35
	v_cvt_pk_bf16_f32 v5, v36, v37
	v_lshl_add_u64 v[12:13], v[12:13], 0, v[70:71]
	v_rcp_f32_e32 v32, v32
	v_rcp_f32_e32 v30, v30
	v_rcp_f32_e32 v31, v31
	v_rcp_f32_e32 v33, v33
	global_store_dwordx4 v[12:13], v[2:5], off
	s_andn2_b64 vcc, exec, s[38:39]
	v_pk_mul_f32 v[16:17], v[16:17], v[30:31]
	v_cvt_pk_bf16_f32 v2, v6, v7
	v_or_b32_e32 v6, 1, v18
	v_mad_i64_i32 v[6:7], s[30:31], v6, s49, v[10:11]
	v_cvt_pk_bf16_f32 v3, v8, v9
	v_cvt_pk_bf16_f32 v4, v38, v39
	v_cvt_pk_bf16_f32 v5, v40, v41
	v_lshl_add_u64 v[6:7], v[6:7], 0, v[70:71]
	v_subrev_u32_e32 v6, s12, v6
	global_store_dwordx4 v6, v[2:5], s[12:13]
	v_or_b32_e32 v6, 2, v18
	v_pk_mul_f32 v[14:15], v[14:15], v[32:33]
	v_mad_i64_i32 v[6:7], s[30:31], v6, s49, v[10:11]
	v_cvt_pk_bf16_f32 v2, v14, v15
	v_cvt_pk_bf16_f32 v3, v16, v17
	v_cvt_pk_bf16_f32 v4, v48, v49
	v_cvt_pk_bf16_f32 v5, v46, v47
	v_lshl_add_u64 v[6:7], v[6:7], 0, v[70:71]
	v_subrev_u32_e32 v6, s12, v6
	global_store_dwordx4 v6, v[2:5], s[12:13]
	v_or_b32_e32 v6, 3, v18
	v_mad_i64_i32 v[6:7], s[30:31], v6, s49, v[10:11]
	v_cvt_pk_bf16_f32 v2, v22, v23
	v_cvt_pk_bf16_f32 v3, v24, v25
	v_cvt_pk_bf16_f32 v4, v56, v57
	v_cvt_pk_bf16_f32 v5, v54, v55
	v_lshl_add_u64 v[6:7], v[6:7], 0, v[70:71]
	s_mov_b64 s[38:39], -1
	global_store_dwordx4 v[6:7], v[2:5], off
	s_cbranch_vccnz .LBB0_760
	s_andn2_b64 vcc, exec, s[14:15]
	s_cbranch_vccnz .LBB0_759
	s_barrier
	s_branch .LBB0_759

.LBB0_839:
	s_lshl_b32 s20, s40, 14
	s_add_i32 s30, s20, 0
	s_sext_i32_i16 s20, s38
	s_lshl_b32 s20, s20, 6
	s_ashr_i32 s21, s20, 31
	s_mul_i32 s23, s14, s21
	s_mul_hi_u32 s38, s14, s20
	s_add_i32 s23, s38, s23
	s_mul_i32 s15, s15, s20
	s_add_i32 s39, s23, s15
	s_mul_i32 s38, s14, s20
	s_lshl_b64 s[38:39], s[38:39], 2
	s_add_u32 s15, s16, s38
	s_addc_u32 s38, s17, s39
	s_ashr_i32 s23, s22, 31
	s_lshl_b64 s[16:17], s[22:23], 2
	v_and_b32_e32 v67, 15, v66
	s_add_u32 s16, s15, s16
	s_waitcnt vmcnt(4)
	v_lshrrev_b32_e32 v69, 3, v0
	v_bfe_u32 v130, v0, 3, 3
	s_addc_u32 s17, s38, s17
	v_and_b32_e32 v131, 48, v66
	v_lshlrev_b32_e32 v0, 4, v67
	s_mov_b64 s[78:79], s[16:17]
	v_mov_b32_e32 v58, v0
	v_mul_u32_u24_e32 v0, s14, v131
	v_lshlrev_b32_e32 v0, 2, v0
	v_or_b32_e32 v133, 1, v131
	v_add_u32_e32 v2, v58, v0
	v_mul_u32_u24_e32 v0, s14, v133
	v_lshlrev_b32_e32 v0, 2, v0
	v_or_b32_e32 v135, 2, v131
	v_add_u32_e32 v4, v58, v0
	v_mul_u32_u24_e32 v0, s14, v135
	v_lshlrev_b32_e32 v0, 2, v0
	v_or_b32_e32 v137, 3, v131
	v_add_u32_e32 v10, v58, v0
	v_mul_u32_u24_e32 v0, s14, v137
	v_lshlrev_b32_e32 v0, 2, v0
	v_or_b32_e32 v139, 4, v131
	v_add_u32_e32 v12, v58, v0
	v_mul_u32_u24_e32 v0, s14, v139
	v_lshlrev_b32_e32 v0, 2, v0
	v_or_b32_e32 v141, 5, v131
	v_add_u32_e32 v18, v58, v0
	v_mul_u32_u24_e32 v0, s14, v141
	v_lshlrev_b32_e32 v0, 2, v0
	v_or_b32_e32 v143, 6, v131
	v_add_u32_e32 v20, v58, v0
	v_mul_u32_u24_e32 v0, s14, v143
	v_lshlrev_b32_e32 v0, 2, v0
	v_or_b32_e32 v145, 7, v131
	v_add_u32_e32 v26, v58, v0
	v_mul_u32_u24_e32 v0, s14, v145
	v_lshlrev_b32_e32 v0, 2, v0
	v_or_b32_e32 v148, 8, v131
	v_add_u32_e32 v28, v58, v0
	v_mul_u32_u24_e32 v0, s14, v148
	v_lshlrev_b32_e32 v0, 2, v0
	v_or_b32_e32 v149, 9, v131
	v_add_u32_e32 v34, v58, v0
	v_mul_u32_u24_e32 v0, s14, v149
	v_lshlrev_b32_e32 v0, 2, v0
	v_or_b32_e32 v150, 10, v131
	v_add_u32_e32 v36, v58, v0
	v_mul_u32_u24_e32 v0, s14, v150
	v_lshlrev_b32_e32 v0, 2, v0
	v_or_b32_e32 v151, 11, v131
	v_add_u32_e32 v42, v58, v0
	v_mul_u32_u24_e32 v0, s14, v151
	v_lshlrev_b32_e32 v0, 2, v0
	v_or_b32_e32 v152, 12, v131
	v_add_u32_e32 v44, v58, v0
	v_mul_u32_u24_e32 v0, s14, v152
	v_lshlrev_b32_e32 v0, 2, v0
	v_or_b32_e32 v153, 13, v131
	v_add_u32_e32 v50, v58, v0
	v_mul_u32_u24_e32 v0, s14, v153
	v_lshlrev_b32_e32 v0, 2, v0
	v_or_b32_e32 v154, 14, v131
	v_add_u32_e32 v52, v58, v0
	v_mul_u32_u24_e32 v0, s14, v154
	v_lshlrev_b32_e32 v0, 2, v0
	v_or_b32_e32 v155, 15, v131
	v_add_u32_e32 v60, v58, v0
	v_mul_u32_u24_e32 v0, s14, v155
	v_lshlrev_b32_e32 v0, 2, v0
	v_add_u32_e32 v58, v58, v0
	global_load_dwordx4 v[6:9], v2, s[78:79] nt
	s_nop 0
	global_load_dwordx4 v[2:5], v4, s[78:79] nt
	s_nop 0
	global_load_dwordx4 v[14:17], v10, s[78:79] nt
	s_nop 0
	global_load_dwordx4 v[10:13], v12, s[78:79] nt
	s_nop 0
	global_load_dwordx4 v[22:25], v18, s[78:79] nt
	s_nop 0
	global_load_dwordx4 v[18:21], v20, s[78:79] nt
	s_nop 0
	global_load_dwordx4 v[30:33], v26, s[78:79] nt
	s_nop 0
	global_load_dwordx4 v[26:29], v28, s[78:79] nt
	s_nop 0
	global_load_dwordx4 v[38:41], v34, s[78:79] nt
	s_nop 0
	global_load_dwordx4 v[34:37], v36, s[78:79] nt
	s_nop 0
	global_load_dwordx4 v[46:49], v42, s[78:79] nt
	s_nop 0
	global_load_dwordx4 v[42:45], v44, s[78:79] nt
	s_nop 0
	global_load_dwordx4 v[54:57], v50, s[78:79] nt
	s_nop 0
	global_load_dwordx4 v[50:53], v52, s[78:79] nt
	s_nop 0
	global_load_dwordx4 v[62:65], v60, s[78:79] nt
	s_nop 0
	global_load_dwordx4 v[58:61], v58, s[78:79] nt
	s_ashr_i32 s14, s31, 31
	s_mul_hi_u32 s15, s31, s63
	s_mul_i32 s14, s14, s63
	s_add_i32 s15, s15, s14
	s_mul_i32 s14, s31, s63
	s_lshl_b64 s[14:15], s[14:15], 1
	v_and_b32_e32 v68, 6, v69
	v_and_b32_e32 v70, 7, v66
	v_or_b32_e32 v132, 8, v130
	v_or_b32_e32 v134, 16, v130
	v_or_b32_e32 v136, 24, v130
	v_or_b32_e32 v140, 40, v130
	v_or_b32_e32 v142, 48, v130
	v_or_b32_e32 v144, 56, v130
	s_add_u32 s14, s12, s14
	v_bitop3_b32 v71, v69, v70, 6 bitop3:0x6c
	v_bitop3_b32 v68, v68, v70, 1 bitop3:0x36
	v_bfe_u32 v69, v69, 2, 1
	v_lshrrev_b32_e32 v74, 2, v132
	v_lshrrev_b32_e32 v76, 2, v134
	v_lshrrev_b32_e32 v78, 2, v136
	v_lshrrev_b32_e32 v81, 2, v140
	v_lshrrev_b32_e32 v83, 2, v142
	v_lshrrev_b32_e32 v85, 2, v144
	s_addc_u32 s15, s13, s15
	s_lshl_b64 s[12:13], s[20:21], 1
	v_lshlrev_b32_e32 v70, 4, v68
	v_lshlrev_b32_e32 v68, 3, v66
	v_xor_b32_e32 v69, v69, v66
	v_xor_b32_e32 v74, v74, v66
	v_xor_b32_e32 v76, v76, v66
	v_xor_b32_e32 v78, v78, v66
	v_xor_b32_e32 v81, v81, v66
	v_xor_b32_e32 v83, v83, v66
	v_xor_b32_e32 v66, v85, v66
	s_add_u32 s12, s14, s12
	v_lshlrev_b32_e32 v69, 4, v69
	v_lshlrev_b32_e32 v74, 4, v74
	v_lshlrev_b32_e32 v76, 4, v76
	v_lshlrev_b32_e32 v78, 4, v78
	v_or_b32_e32 v138, 32, v130
	v_lshlrev_b32_e32 v81, 4, v81
	v_lshlrev_b32_e32 v83, 4, v83
	v_lshlrev_b32_e32 v66, 4, v66
	v_lshlrev_b32_e32 v0, 2, v67
	s_addc_u32 s13, s15, s13
	v_lshl_add_u32 v67, v67, 9, s30
	v_lshlrev_b32_e32 v71, 4, v71
	v_and_b32_e32 v68, 56, v68
	v_lshl_add_u32 v72, v130, 7, s30
	v_and_b32_e32 v69, 0x70, v69
	v_lshl_add_u32 v73, v132, 7, s30
	v_and_b32_e32 v74, 0x70, v74
	v_lshl_add_u32 v75, v134, 7, s30
	v_and_b32_e32 v76, 0x70, v76
	v_lshl_add_u32 v77, v136, 7, s30
	v_and_b32_e32 v78, 0x70, v78
	v_lshl_add_u32 v79, v138, 7, s30
	v_lshl_add_u32 v80, v140, 7, s30
	v_and_b32_e32 v81, 0x70, v81
	v_lshl_add_u32 v82, v142, 7, s30
	v_and_b32_e32 v83, 0x70, v83
	v_lshl_add_u32 v84, v144, 7, s30
	v_and_b32_e32 v66, 0x70, v66
	s_add_i32 s64, s2, 0x400
	v_lshlrev_b32_e32 v0, 2, v0
	v_add_u32_e32 v156, v67, v71
	v_add_u32_e32 v157, v67, v70
	v_lshlrev_b32_e32 v146, 1, v68
	v_add_u32_e32 v158, v72, v69
	v_add_u32_e32 v159, v73, v74
	v_add_u32_e32 v160, v75, v76
	v_add_u32_e32 v161, v77, v78
	v_add_u32_e32 v162, v79, v69
	v_add_u32_e32 v163, v80, v81
	v_add_u32_e32 v164, v82, v83
	v_add_u32_e32 v165, v84, v66
	s_mov_b64 s[16:17], s[12:13]
	s_mov_b32 s65, s63
	s_branch .LBB0_842
.LBB0_840:
	s_sext_i32_i16 s31, s31
	s_lshl_b32 s38, s31, 6
	s_ashr_i32 s39, s38, 31
	s_mul_i32 s31, s22, s39
	s_mul_hi_u32 s41, s22, s38
	s_add_i32 s31, s41, s31
	s_mul_i32 s23, s23, s38
	s_add_i32 s43, s31, s23
	s_mul_i32 s42, s22, s38
	s_lshl_b64 s[42:43], s[42:43], 2
	s_add_u32 s23, s20, s42
	s_addc_u32 s31, s21, s43
	s_ashr_i32 s41, s40, 31
	s_lshl_b64 s[20:21], s[40:41], 2
	s_add_u32 s20, s23, s20
	s_addc_u32 s21, s31, s21
	v_mul_u32_u24_e32 v66, s22, v131
	v_mul_u32_u24_e32 v68, s22, v133
	v_mul_u32_u24_e32 v74, s22, v135
	v_mul_u32_u24_e32 v76, s22, v137
	v_mul_u32_u24_e32 v82, s22, v139
	v_mul_u32_u24_e32 v84, s22, v141
	v_mul_u32_u24_e32 v90, s22, v143
	v_mul_u32_u24_e32 v92, s22, v145
	v_mul_u32_u24_e32 v98, s22, v148
	v_mul_u32_u24_e32 v100, s22, v149
	v_mul_u32_u24_e32 v106, s22, v150
	v_mul_u32_u24_e32 v108, s22, v151
	v_mul_u32_u24_e32 v114, s22, v152
	v_mul_u32_u24_e32 v116, s22, v153
	v_mul_u32_u24_e32 v124, s22, v154
	v_mul_u32_u24_e32 v126, s22, v155
	s_mov_b64 s[80:81], s[20:21]
	v_mov_b32_e32 v122, v0
	v_lshlrev_b32_e32 v66, 2, v66
	v_mov_b32_e32 v67, v1
	v_lshlrev_b32_e32 v68, 2, v68
	v_mov_b32_e32 v69, v1
	v_lshlrev_b32_e32 v74, 2, v74
	v_mov_b32_e32 v75, v1
	v_lshlrev_b32_e32 v76, 2, v76
	v_mov_b32_e32 v77, v1
	v_lshlrev_b32_e32 v82, 2, v82
	v_mov_b32_e32 v83, v1
	v_lshlrev_b32_e32 v84, 2, v84
	v_mov_b32_e32 v85, v1
	v_lshlrev_b32_e32 v90, 2, v90
	v_mov_b32_e32 v91, v1
	v_lshlrev_b32_e32 v92, 2, v92
	v_mov_b32_e32 v93, v1
	v_lshlrev_b32_e32 v98, 2, v98
	v_mov_b32_e32 v99, v1
	v_lshlrev_b32_e32 v100, 2, v100
	v_mov_b32_e32 v101, v1
	v_lshlrev_b32_e32 v106, 2, v106
	v_mov_b32_e32 v107, v1
	v_lshlrev_b32_e32 v108, 2, v108
	v_mov_b32_e32 v109, v1
	v_lshlrev_b32_e32 v114, 2, v114
	v_mov_b32_e32 v115, v1
	v_lshlrev_b32_e32 v116, 2, v116
	v_mov_b32_e32 v117, v1
	v_lshlrev_b32_e32 v124, 2, v124
	v_mov_b32_e32 v125, v1
	v_lshlrev_b32_e32 v126, 2, v126
	v_mov_b32_e32 v127, v1
	v_add_u32_e32 v66, v122, v66
	v_add_u32_e32 v70, v122, v68
	v_add_u32_e32 v74, v122, v74
	v_add_u32_e32 v78, v122, v76
	v_add_u32_e32 v82, v122, v82
	v_add_u32_e32 v86, v122, v84
	v_add_u32_e32 v90, v122, v90
	v_add_u32_e32 v94, v122, v92
	v_add_u32_e32 v98, v122, v98
	v_add_u32_e32 v102, v122, v100
	v_add_u32_e32 v106, v122, v106
	v_add_u32_e32 v110, v122, v108
	v_add_u32_e32 v114, v122, v114
	v_add_u32_e32 v118, v122, v116
	v_add_u32_e32 v124, v122, v124
	v_add_u32_e32 v126, v122, v126
	global_load_dwordx4 v[66:69], v66, s[80:81] nt
	s_nop 0
	global_load_dwordx4 v[70:73], v70, s[80:81] nt
	s_nop 0
	global_load_dwordx4 v[74:77], v74, s[80:81] nt
	s_nop 0
	global_load_dwordx4 v[78:81], v78, s[80:81] nt
	s_nop 0
	global_load_dwordx4 v[82:85], v82, s[80:81] nt
	s_nop 0
	global_load_dwordx4 v[86:89], v86, s[80:81] nt
	s_nop 0
	global_load_dwordx4 v[90:93], v90, s[80:81] nt
	s_nop 0
	global_load_dwordx4 v[94:97], v94, s[80:81] nt
	s_nop 0
	global_load_dwordx4 v[98:101], v98, s[80:81] nt
	s_nop 0
	global_load_dwordx4 v[102:105], v102, s[80:81] nt
	s_nop 0
	global_load_dwordx4 v[106:109], v106, s[80:81] nt
	s_nop 0
	global_load_dwordx4 v[110:113], v110, s[80:81] nt
	s_nop 0
	global_load_dwordx4 v[114:117], v114, s[80:81] nt
	s_nop 0
	global_load_dwordx4 v[118:121], v118, s[80:81] nt
	s_nop 0
	global_load_dwordx4 v[122:125], v124, s[80:81] nt
	s_nop 0
	global_load_dwordx4 v[126:129], v126, s[80:81] nt
	s_ashr_i32 s20, s30, 31
	s_mul_hi_u32 s21, s30, s65
	s_mul_i32 s20, s20, s65
	s_add_i32 s21, s21, s20
	s_mul_i32 s20, s30, s65
	s_lshl_b64 s[20:21], s[20:21], 1
	s_add_u32 s20, s16, s20
	s_addc_u32 s21, s17, s21
	s_lshl_b64 s[16:17], s[38:39], 1
	s_add_u32 s16, s20, s16
	s_addc_u32 s17, s21, s17
.LBB0_841:
	s_waitcnt vmcnt(14)
	v_cvt_pk_bf16_f32 v170, v6, v2
	s_waitcnt vmcnt(12)
	v_cvt_pk_bf16_f32 v171, v14, v10
	s_waitcnt vmcnt(10)
	v_cvt_pk_bf16_f32 v172, v22, v18
	s_waitcnt vmcnt(8)
	v_cvt_pk_bf16_f32 v173, v30, v26
	s_waitcnt vmcnt(6)
	v_cvt_pk_bf16_f32 v174, v38, v34
	s_waitcnt vmcnt(4)
	v_cvt_pk_bf16_f32 v175, v46, v42
	s_waitcnt vmcnt(2)
	v_cvt_pk_bf16_f32 v176, v54, v50
	s_waitcnt vmcnt(0)
	v_cvt_pk_bf16_f32 v177, v62, v58
	ds_write_b128 v156, v[170:173]
	ds_write_b128 v157, v[174:177]
	v_cvt_pk_bf16_f32 v170, v7, v3
	v_cvt_pk_bf16_f32 v171, v15, v11
	v_cvt_pk_bf16_f32 v172, v23, v19
	v_cvt_pk_bf16_f32 v173, v31, v27
	v_cvt_pk_bf16_f32 v174, v39, v35
	v_cvt_pk_bf16_f32 v175, v47, v43
	v_cvt_pk_bf16_f32 v176, v55, v51
	v_cvt_pk_bf16_f32 v177, v63, v59
	ds_write_b128 v156, v[170:173] offset:128
	ds_write_b128 v157, v[174:177] offset:128
	v_cvt_pk_bf16_f32 v170, v8, v4
	v_cvt_pk_bf16_f32 v171, v16, v12
	v_cvt_pk_bf16_f32 v172, v24, v20
	v_cvt_pk_bf16_f32 v173, v32, v28
	v_cvt_pk_bf16_f32 v2, v9, v5
	v_cvt_pk_bf16_f32 v3, v17, v13
	v_cvt_pk_bf16_f32 v4, v25, v21
	v_cvt_pk_bf16_f32 v5, v33, v29
	v_cvt_pk_bf16_f32 v174, v40, v36
	v_cvt_pk_bf16_f32 v175, v48, v44
	v_cvt_pk_bf16_f32 v176, v56, v52
	v_cvt_pk_bf16_f32 v177, v64, v60
	ds_write_b128 v156, v[170:173] offset:256
	ds_write_b128 v157, v[174:177] offset:256
	v_cvt_pk_bf16_f32 v6, v41, v37
	v_cvt_pk_bf16_f32 v7, v49, v45
	v_cvt_pk_bf16_f32 v8, v57, v53
	v_cvt_pk_bf16_f32 v9, v65, v61
	ds_write_b128 v156, v[2:5] offset:384
	ds_write_b128 v157, v[6:9] offset:384
	s_waitcnt lgkmcnt(0)
	v_mov_b32_e32 v147, v1
	ds_read_b128 v[2:5], v158
	s_mov_b64 s[82:83], s[12:13]
	v_mov_b32_e32 v10, v146
	v_mad_u64_u32 v[6:7], s[12:13], s63, v130, 0
	v_lshl_add_u32 v12, v6, 1, v10
	ds_read_b128 v[6:9], v159
	s_waitcnt lgkmcnt(1)
	global_store_dwordx4 v12, v[2:5], s[82:83]
	v_mov_b64_e32 v[58:59], v[126:127]
	v_mov_b64_e32 v[62:63], v[122:123]
	v_mad_u64_u32 v[2:3], s[12:13], s63, v132, 0
	v_lshl_add_u32 v2, v2, 1, v10
	s_waitcnt lgkmcnt(0)
	global_store_dwordx4 v2, v[6:9], s[82:83]
	ds_read_b128 v[2:5], v160
	v_mov_b64_e32 v[50:51], v[118:119]
	v_mad_u64_u32 v[6:7], s[12:13], s63, v134, 0
	v_lshl_add_u32 v12, v6, 1, v10
	ds_read_b128 v[6:9], v161
	s_waitcnt lgkmcnt(1)
	global_store_dwordx4 v12, v[2:5], s[82:83]
	v_mov_b64_e32 v[54:55], v[114:115]
	v_mov_b64_e32 v[42:43], v[110:111]
	v_mad_u64_u32 v[2:3], s[12:13], s63, v136, 0
	v_lshl_add_u32 v2, v2, 1, v10
	s_waitcnt lgkmcnt(0)
	global_store_dwordx4 v2, v[6:9], s[82:83]
	ds_read_b128 v[2:5], v162
	v_mov_b64_e32 v[46:47], v[106:107]
	v_mad_u64_u32 v[6:7], s[12:13], s63, v138, 0
	v_lshl_add_u32 v12, v6, 1, v10
	ds_read_b128 v[6:9], v163
	s_waitcnt lgkmcnt(1)
	global_store_dwordx4 v12, v[2:5], s[82:83]
	v_mov_b64_e32 v[34:35], v[102:103]
	v_mov_b64_e32 v[38:39], v[98:99]
	v_mad_u64_u32 v[2:3], s[12:13], s63, v140, 0
	v_lshl_add_u32 v2, v2, 1, v10
	s_waitcnt lgkmcnt(0)
	global_store_dwordx4 v2, v[6:9], s[82:83]
	ds_read_b128 v[2:5], v164
	v_mov_b64_e32 v[26:27], v[94:95]
	v_mad_u64_u32 v[6:7], s[12:13], s63, v142, 0
	v_lshl_add_u32 v12, v6, 1, v10
	ds_read_b128 v[6:9], v165
	s_waitcnt lgkmcnt(1)
	global_store_dwordx4 v12, v[2:5], s[82:83]
	v_mov_b64_e32 v[30:31], v[90:91]
	v_mov_b64_e32 v[18:19], v[86:87]
	v_mad_u64_u32 v[2:3], s[12:13], s63, v144, 0
	v_lshl_add_u32 v2, v2, 1, v10
	s_waitcnt lgkmcnt(0)
	global_store_dwordx4 v2, v[6:9], s[82:83]
	s_waitcnt lgkmcnt(0)
	v_mov_b64_e32 v[22:23], v[82:83]
	v_mov_b64_e32 v[10:11], v[78:79]
	v_mov_b64_e32 v[14:15], v[74:75]
	v_mov_b64_e32 v[2:3], v[70:71]
	v_mov_b64_e32 v[6:7], v[66:67]
	s_addk_i32 s64, 0x400
	s_andn2_b64 vcc, exec, s[14:15]
	v_mov_b64_e32 v[60:61], v[128:129]
	v_mov_b64_e32 v[64:65], v[124:125]
	v_mov_b64_e32 v[52:53], v[120:121]
	v_mov_b64_e32 v[56:57], v[116:117]
	v_mov_b64_e32 v[44:45], v[112:113]
	v_mov_b64_e32 v[48:49], v[108:109]
	v_mov_b64_e32 v[36:37], v[104:105]
	v_mov_b64_e32 v[40:41], v[100:101]
	v_mov_b64_e32 v[28:29], v[96:97]
	v_mov_b64_e32 v[32:33], v[92:93]
	v_mov_b64_e32 v[20:21], v[88:89]
	v_mov_b64_e32 v[24:25], v[84:85]
	v_mov_b64_e32 v[12:13], v[80:81]
	v_mov_b64_e32 v[16:17], v[76:77]
	v_mov_b64_e32 v[4:5], v[72:73]
	v_mov_b64_e32 v[8:9], v[68:69]
	s_mov_b64 s[12:13], s[16:17]
	s_mov_b32 s63, s65
	s_cbranch_vccz .LBB0_875
